# also: D3 state wave applies the per-step decay (S *= gl) as single v_mul_f32 in the shadow of the first MFMA block instead of 32 v_pk_mul_f32 after the v_new hand-off
# speedup vs baseline: 1.0259x; 1.0064x over previous
; #define MFMA32(a, b, c) __builtin_amdgcn_mfma_f32_32x32x16_bf16((a), (b), (c), 0, 0, 0)
; #define D3_BAR() do { asm volatile("s_waitcnt lgkmcnt(0)" ::: "memory"); __builtin_amdgcn_s_barrier(); asm volatile("" ::: "memory"); } while (0)
; DI void d3_block(const Params& P, int bh, int vs, LAS unsigned char* lds, int wave, int lane, int tid) {
;     ...
; #pragma unroll
;             for (int G = 0; G < 4; ++G) { S[0] = MFMA32(fk[G], Vb[G], S[0]); S[1] = MFMA32(fk[4 + G], Vb[G], S[1]); S[2] = MFMA32(fk[8 + G], Vb[G], S[2]); S[3] = MFMA32(fk[12 + G], Vb[G], S[3]); }
;             __builtin_amdgcn_sched_barrier(0);
; #pragma unroll
;             for (int j = 0; j < 4; ++j) { Sb[2 * j] = pack8(S[j], 0); Sb[2 * j + 1] = pack8(S[j], 1); exSb[(2 * j) * 64] = Sb[2 * j]; exSb[(2 * j + 1) * 64] = Sb[2 * j + 1]; }
;             gl = gl_next;
;             D3_BAR();
.LBB0_368:
	s_or_b64 exec, exec, s[4:5]
	s_waitcnt vmcnt(0)
	s_waitcnt lgkmcnt(14)
	v_mfma_f32_32x32x16_bf16 v[0:15], v[162:165], v[154:157], v[0:15]
	v_mfma_f32_32x32x16_bf16 v[16:31], v[158:161], v[154:157], v[16:31]
	s_waitcnt lgkmcnt(11)
	v_mfma_f32_32x32x16_bf16 v[32:47], v[150:153], v[154:157], v[32:47]
	s_waitcnt lgkmcnt(7)
	v_mfma_f32_32x32x16_bf16 v[48:63], v[146:149], v[154:157], v[48:63]
	v_mfma_f32_32x32x16_bf16 v[0:15], v[130:133], v[72:75], v[0:15]
	v_mfma_f32_32x32x16_bf16 v[16:31], v[134:137], v[72:75], v[16:31]
	v_mfma_f32_32x32x16_bf16 v[32:47], v[138:141], v[72:75], v[32:47]
	s_waitcnt lgkmcnt(6)
	v_mfma_f32_32x32x16_bf16 v[48:63], v[142:145], v[72:75], v[48:63]
	v_mfma_f32_32x32x16_bf16 v[0:15], v[114:117], v[68:71], v[0:15]
	v_mfma_f32_32x32x16_bf16 v[16:31], v[118:121], v[68:71], v[16:31]
	v_mfma_f32_32x32x16_bf16 v[32:47], v[122:125], v[68:71], v[32:47]
	s_waitcnt lgkmcnt(5)
	v_mfma_f32_32x32x16_bf16 v[48:63], v[126:129], v[68:71], v[48:63]
	v_mfma_f32_32x32x16_bf16 v[0:15], v[98:101], v[64:67], v[0:15]
	v_mfma_f32_32x32x16_bf16 v[16:31], v[102:105], v[64:67], v[16:31]
	v_mfma_f32_32x32x16_bf16 v[32:47], v[106:109], v[64:67], v[32:47]
	s_waitcnt lgkmcnt(4)
	v_mfma_f32_32x32x16_bf16 v[48:63], v[110:113], v[64:67], v[48:63]
	s_nop 7
	v_cvt_pk_bf16_f32 v98, v0, v1
	v_cvt_pk_bf16_f32 v99, v2, v3
	v_cvt_pk_bf16_f32 v100, v4, v5
	v_cvt_pk_bf16_f32 v101, v6, v7
	v_cvt_pk_bf16_f32 v106, v16, v17
	v_cvt_pk_bf16_f32 v107, v18, v19
	v_cvt_pk_bf16_f32 v108, v20, v21
	v_cvt_pk_bf16_f32 v109, v22, v23
	v_cvt_pk_bf16_f32 v114, v32, v33
	v_cvt_pk_bf16_f32 v115, v34, v35
	v_cvt_pk_bf16_f32 v116, v36, v37
	v_cvt_pk_bf16_f32 v117, v38, v39
	v_cvt_pk_bf16_f32 v122, v48, v49
	v_cvt_pk_bf16_f32 v123, v50, v51
	v_cvt_pk_bf16_f32 v124, v52, v53
	v_cvt_pk_bf16_f32 v125, v54, v55
	v_cvt_pk_bf16_f32 v102, v8, v9
	v_cvt_pk_bf16_f32 v103, v10, v11
	v_cvt_pk_bf16_f32 v104, v12, v13
	v_cvt_pk_bf16_f32 v105, v14, v15
	ds_write_b128 v166, v[98:101]
	ds_write_b128 v166, v[102:105] offset:1024
	v_cvt_pk_bf16_f32 v110, v24, v25
	v_cvt_pk_bf16_f32 v111, v26, v27
	v_cvt_pk_bf16_f32 v112, v28, v29
	v_cvt_pk_bf16_f32 v113, v30, v31
	ds_write_b128 v166, v[106:109] offset:2048
	ds_write_b128 v166, v[110:113] offset:3072
	v_cvt_pk_bf16_f32 v118, v40, v41
	v_cvt_pk_bf16_f32 v119, v42, v43
	v_cvt_pk_bf16_f32 v120, v44, v45
	v_cvt_pk_bf16_f32 v121, v46, v47
	ds_write_b128 v166, v[114:117] offset:4096
	ds_write_b128 v166, v[118:121] offset:5120
	v_cvt_pk_bf16_f32 v126, v56, v57
	v_cvt_pk_bf16_f32 v127, v58, v59
	v_cvt_pk_bf16_f32 v128, v60, v61
	v_cvt_pk_bf16_f32 v129, v62, v63
	ds_write_b128 v166, v[122:125] offset:6144
	ds_write_b128 v166, v[126:129] offset:7168
	s_waitcnt lgkmcnt(0)
	s_barrier
	s_cmpk_eq_i32 s8, 0x80
	v_mov_b32_e32 v96, v170
	s_cbranch_scc1 .LBB0_371
; #define LAS __attribute__((address_space(3)))
; #define MFMA32(a, b, c) __builtin_amdgcn_mfma_f32_32x32x16_bf16((a), (b), (c), 0, 0, 0)
; DI float bflo(unsigned u) { return __uint_as_float(u << 16); }
; DI float bfhi(unsigned u) { return __uint_as_float(u & 0xffff0000u); }
; DI void d3_block(const Params& P, int bh, int vs, LAS unsigned char* lds, int wave, int lane, int tid) {
;     ...
;         for (int n = 0; n < 128; ++n) {
;             const LAS unsigned char* sb = lds + (n & 1) * D3_SLOT;
;             const LAS bf16x8* fNW = (const LAS bf16x8*)sb + lane; const LAS bf16x8* fKD = (const LAS bf16x8*)(sb + 40960) + lane;
;             const LAS u32x4* fU = (const LAS u32x4*)(sb + 57344) + lane * 2;
;             const float gl_next = GL[(n + 1) & 127];
;             bf16x8 fw[16];
; #pragma unroll
;             for (int q = 0; q < 16; ++q) fw[q] = fNW[q * 64];
;             f32x16 vt[2];
; #pragma unroll
;             for (int t = 0; t < 2; ++t) { const u32x4 a = fU[t * 128], b2 = fU[t * 128 + 1];
;                 vt[t][0] = bflo(a.x); vt[t][1] = bfhi(a.x); vt[t][2] = bflo(a.y); vt[t][3] = bfhi(a.y); vt[t][4] = bflo(a.z); vt[t][5] = bfhi(a.z); vt[t][6] = bflo(a.w); vt[t][7] = bfhi(a.w);
;                 vt[t][8] = bflo(b2.x); vt[t][9] = bfhi(b2.x); vt[t][10] = bflo(b2.y); vt[t][11] = bfhi(b2.y); vt[t][12] = bflo(b2.z); vt[t][13] = bfhi(b2.z); vt[t][14] = bflo(b2.w); vt[t][15] = bfhi(b2.w); }
;             __builtin_amdgcn_sched_barrier(0);
; #pragma unroll
;             for (int G = 0; G < 8; ++G) {
;                 vt[0] = MFMA32(fw[G], Sb[G], vt[0]); vt[1] = MFMA32(fw[8 + G], Sb[G], vt[1]);
;                 if (G < 4) {
; #pragma unroll
;                     for (int i = 0; i < 16; ++i) S[G][i] *= gl; } }
;             __builtin_amdgcn_sched_barrier(0);
;             bf16x8 fk[16];
; #pragma unroll
;             for (int q = 0; q < 16; ++q) fk[q] = fKD[q * 64];
.LBB0_369:
	s_bitcmp1_b32 s8, 0
	s_cselect_b32 s4, 0xf000, 0
	s_add_i32 s8, s8, 1
	s_and_b32 s5, s8, 0x7f
	s_lshl_b32 s5, s5, 2
	v_mov_b32_e32 v64, s5
	global_load_dword v170, v64, s[0:1]
	s_add_i32 s4, s4, 0
	v_lshl_add_u32 v64, v240, 4, s4
	ds_read_b128 v[130:133], v64
	ds_read_b128 v[134:137], v64 offset:1024
	ds_read_b128 v[138:141], v64 offset:2048
	ds_read_b128 v[142:145], v64 offset:3072
	ds_read_b128 v[146:149], v64 offset:4096
	ds_read_b128 v[150:153], v64 offset:5120
	ds_read_b128 v[154:157], v64 offset:6144
	ds_read_b128 v[158:161], v64 offset:7168
	ds_read_b128 v[162:165], v64 offset:8192
	ds_read_b128 v[172:175], v64 offset:9216
	ds_read_b128 v[176:179], v64 offset:10240
	ds_read_b128 v[184:187], v64 offset:11264
	v_add_u32_e32 v171, s4, v168
	ds_read_b128 v[68:71], v171 offset:57344
	ds_read_b128 v[196:199], v64 offset:12288
	ds_read_b128 v[200:203], v64 offset:13312
	ds_read_b128 v[204:207], v64 offset:14336
	ds_read_b128 v[208:211], v64 offset:15360
	ds_read_b128 v[76:79], v171 offset:57360
	ds_read_b128 v[84:87], v171 offset:59392
	ds_read_b128 v[92:95], v171 offset:59408
	s_waitcnt lgkmcnt(0)
	v_lshlrev_b32_e32 v64, 16, v68
	v_and_b32_e32 v65, 0xffff0000, v68
	v_lshlrev_b32_e32 v66, 16, v69
	v_and_b32_e32 v67, 0xffff0000, v69
	v_lshlrev_b32_e32 v68, 16, v70
	v_and_b32_e32 v69, 0xffff0000, v70
	v_lshlrev_b32_e32 v70, 16, v71
	v_and_b32_e32 v71, 0xffff0000, v71
	v_lshlrev_b32_e32 v72, 16, v76
	v_and_b32_e32 v73, 0xffff0000, v76
	v_lshlrev_b32_e32 v74, 16, v77
	v_and_b32_e32 v75, 0xffff0000, v77
	v_lshlrev_b32_e32 v76, 16, v78
	v_and_b32_e32 v77, 0xffff0000, v78
	v_lshlrev_b32_e32 v78, 16, v79
	v_and_b32_e32 v79, 0xffff0000, v79
	v_lshlrev_b32_e32 v80, 16, v84
	v_and_b32_e32 v81, 0xffff0000, v84
	v_lshlrev_b32_e32 v82, 16, v85
	v_and_b32_e32 v83, 0xffff0000, v85
	v_lshlrev_b32_e32 v84, 16, v86
	v_and_b32_e32 v85, 0xffff0000, v86
	v_lshlrev_b32_e32 v86, 16, v87
	v_and_b32_e32 v87, 0xffff0000, v87
	v_lshlrev_b32_e32 v88, 16, v92
	v_and_b32_e32 v89, 0xffff0000, v92
	v_lshlrev_b32_e32 v90, 16, v93
	v_and_b32_e32 v91, 0xffff0000, v93
	v_lshlrev_b32_e32 v92, 16, v94
	v_and_b32_e32 v93, 0xffff0000, v94
	v_lshlrev_b32_e32 v94, 16, v95
	v_and_b32_e32 v95, 0xffff0000, v95
	v_mfma_f32_32x32x16_bf16 v[64:79], v[130:133], v[98:101], v[64:79]
	v_mul_f32_e32 v0, v96, v0
	v_mul_f32_e32 v1, v96, v1
	v_mul_f32_e32 v2, v96, v2
	v_mul_f32_e32 v3, v96, v3
	v_mfma_f32_32x32x16_bf16 v[80:95], v[162:165], v[98:101], v[80:95]
	v_mul_f32_e32 v4, v96, v4
	v_mul_f32_e32 v5, v96, v5
	v_mul_f32_e32 v6, v96, v6
	v_mul_f32_e32 v7, v96, v7
	v_mfma_f32_32x32x16_bf16 v[64:79], v[134:137], v[102:105], v[64:79]
	v_mul_f32_e32 v8, v96, v8
	v_mul_f32_e32 v9, v96, v9
	v_mul_f32_e32 v10, v96, v10
	v_mul_f32_e32 v11, v96, v11
	v_mfma_f32_32x32x16_bf16 v[80:95], v[172:175], v[102:105], v[80:95]
	v_mul_f32_e32 v12, v96, v12
	v_mul_f32_e32 v13, v96, v13
	v_mul_f32_e32 v14, v96, v14
	v_mul_f32_e32 v15, v96, v15
	v_mfma_f32_32x32x16_bf16 v[64:79], v[138:141], v[106:109], v[64:79]
	v_mul_f32_e32 v16, v96, v16
	v_mul_f32_e32 v17, v96, v17
	v_mul_f32_e32 v18, v96, v18
	v_mul_f32_e32 v19, v96, v19
	v_mfma_f32_32x32x16_bf16 v[80:95], v[176:179], v[106:109], v[80:95]
	v_mul_f32_e32 v20, v96, v20
	v_mul_f32_e32 v21, v96, v21
	v_mul_f32_e32 v22, v96, v22
	v_mul_f32_e32 v23, v96, v23
	v_mfma_f32_32x32x16_bf16 v[64:79], v[142:145], v[110:113], v[64:79]
	v_mul_f32_e32 v24, v96, v24
	v_mul_f32_e32 v25, v96, v25
	v_mul_f32_e32 v26, v96, v26
	v_mul_f32_e32 v27, v96, v27
	v_mfma_f32_32x32x16_bf16 v[80:95], v[184:187], v[110:113], v[80:95]
	v_mul_f32_e32 v28, v96, v28
	v_mul_f32_e32 v29, v96, v29
	v_mul_f32_e32 v30, v96, v30
	v_mul_f32_e32 v31, v96, v31
	v_add_u32_e32 v110, v171, v169
	v_mfma_f32_32x32x16_bf16 v[64:79], v[146:149], v[114:117], v[64:79]
	v_mul_f32_e32 v32, v96, v32
	v_mul_f32_e32 v33, v96, v33
	v_mul_f32_e32 v34, v96, v34
	v_mul_f32_e32 v35, v96, v35
	v_mfma_f32_32x32x16_bf16 v[80:95], v[196:199], v[114:117], v[80:95]
	v_mul_f32_e32 v36, v96, v36
	v_mul_f32_e32 v37, v96, v37
	v_mul_f32_e32 v38, v96, v38
	v_mul_f32_e32 v39, v96, v39
	v_mfma_f32_32x32x16_bf16 v[64:79], v[150:153], v[118:121], v[64:79]
	v_mul_f32_e32 v40, v96, v40
	v_mul_f32_e32 v41, v96, v41
	v_mul_f32_e32 v42, v96, v42
	v_mul_f32_e32 v43, v96, v43
	v_mfma_f32_32x32x16_bf16 v[80:95], v[200:203], v[118:121], v[80:95]
	v_mul_f32_e32 v44, v96, v44
	v_mul_f32_e32 v45, v96, v45
	v_mul_f32_e32 v46, v96, v46
	v_mul_f32_e32 v47, v96, v47
	v_mfma_f32_32x32x16_bf16 v[64:79], v[154:157], v[122:125], v[64:79]
	v_mul_f32_e32 v48, v96, v48
	v_mul_f32_e32 v49, v96, v49
	v_mul_f32_e32 v50, v96, v50
	v_mul_f32_e32 v51, v96, v51
	v_mfma_f32_32x32x16_bf16 v[80:95], v[204:207], v[122:125], v[80:95]
	v_mul_f32_e32 v52, v96, v52
	v_mul_f32_e32 v53, v96, v53
	v_mul_f32_e32 v54, v96, v54
	v_mul_f32_e32 v55, v96, v55
	v_mfma_f32_32x32x16_bf16 v[64:79], v[158:161], v[126:129], v[64:79]
	v_mul_f32_e32 v56, v96, v56
	v_mul_f32_e32 v57, v96, v57
	v_mul_f32_e32 v58, v96, v58
	v_mul_f32_e32 v59, v96, v59
	v_mfma_f32_32x32x16_bf16 v[80:95], v[208:211], v[126:129], v[80:95]
	v_mul_f32_e32 v60, v96, v60
	v_mul_f32_e32 v61, v96, v61
	v_mul_f32_e32 v62, v96, v62
	v_mul_f32_e32 v63, v96, v63
	ds_read_b128 v[162:165], v110 offset:40960
	ds_read_b128 v[130:133], v110 offset:41984
	ds_read_b128 v[114:117], v110 offset:43008
	ds_read_b128 v[98:101], v110 offset:44032
	ds_read_b128 v[158:161], v110 offset:45056
	ds_read_b128 v[134:137], v110 offset:46080
	ds_read_b128 v[118:121], v110 offset:47104
	ds_read_b128 v[102:105], v110 offset:48128
	ds_read_b128 v[150:153], v110 offset:49152
	ds_read_b128 v[138:141], v110 offset:50176
	ds_read_b128 v[122:125], v110 offset:51200
	ds_read_b128 v[106:109], v110 offset:52224
	ds_read_b128 v[146:149], v110 offset:53248
	ds_read_b128 v[142:145], v110 offset:54272
	ds_read_b128 v[126:129], v110 offset:55296
	ds_read_b128 v[110:113], v110 offset:56320
	v_cvt_pk_bf16_f32 v154, v64, v65
	v_cvt_pk_bf16_f32 v155, v66, v67
	v_cvt_pk_bf16_f32 v156, v68, v69
	v_cvt_pk_bf16_f32 v157, v70, v71
	v_cvt_pk_bf16_f32 v72, v72, v73
	v_cvt_pk_bf16_f32 v73, v74, v75
	v_cvt_pk_bf16_f32 v74, v76, v77
	v_cvt_pk_bf16_f32 v75, v78, v79
	v_cvt_pk_bf16_f32 v68, v80, v81
	v_cvt_pk_bf16_f32 v69, v82, v83
	v_cvt_pk_bf16_f32 v70, v84, v85
	v_cvt_pk_bf16_f32 v71, v86, v87
	v_cvt_pk_bf16_f32 v64, v88, v89
	v_cvt_pk_bf16_f32 v65, v90, v91
	v_cvt_pk_bf16_f32 v66, v92, v93
	v_cvt_pk_bf16_f32 v67, v94, v95
	ds_write_b128 v167, v[154:157]
	ds_write_b128 v167, v[72:75] offset:1024
	ds_write_b128 v167, v[68:71] offset:2048
	ds_write_b128 v167, v[64:67] offset:3072
	s_waitcnt lgkmcnt(0)
	s_and_saveexec_b64 s[4:5], vcc
	s_cbranch_execz .LBB0_368
	v_readlane_b32 s9, v254, 21
	v_mov_b32_e32 v77, s8
	s_nop 0
	v_mov_b32_e32 v76, s9
	ds_write_b32 v76, v77
	s_branch .LBB0_368
